# v013
# speedup vs baseline: 1.0140x; 1.0022x over previous
; #define SCHED __builtin_amdgcn_sched_barrier(0)
; __device__ __forceinline__ void hyena_item(cchar4* ka, int L, int c, char* smem) {
;     ...
;     const u16* hr = hrev + (size_t)(order * 512 + c) * 4096;
;     {
;       const uint4* hv = (const uint4*)hr;
;       uint4 A = hv[tid];
;       uint4 B = hv[tid < 511 ? tid + 1 : 511];
;       SCHED;
;       if (tid == 511) B = make_uint4(0, 0, 0, 0);
;       unsigned D[8] = {A.x, A.y, A.z, A.w, B.x, B.y, B.z, B.w};
; #pragma unroll
;       for (int q = 0; q < 8; ++q) {
;         const int p = q >> 1;
;         uint4 o;
;         if (q & 1) {
;           o.x = (D[p] >> 16) | (D[p + 1] << 16); o.y = (D[p + 1] >> 16) | (D[p + 2] << 16);
;           o.z = (D[p + 2] >> 16) | (D[p + 3] << 16); o.w = (D[p + 3] >> 16) | (D[p + 4] << 16);
;         } else { o.x = D[p]; o.y = D[p + 1]; o.z = D[p + 2]; o.w = D[p + 3]; }
;         *(uint4*)(cop + q * CSTR + tid * 16) = o;
;       }
;     }
;     __syncthreads();
;     const char* Bs = order == 0 ? Vs : Zs;
;     f32x4 acc[16];
; #pragma unroll
;     for (int i = 0; i < 16; ++i) acc[i] = f32x4{0, 0, 0, 0};
;     {
;       const char* wbase = cop + lane_base - 512 * wave;
;       const char* bbase = Bs + (fr & 7) * USTR + 16 * g;
;       bf16x8 W[16];
; #pragma unroll
;       for (int u = -15; u <= 0; ++u) W[u & 15] = *(const bf16x8*)(wbase + 32 * u);
; #pragma unroll 1
;       for (int k8 = 0; k8 < 8; ++k8) {
; #pragma unroll
;         for (int kk = 0; kk < 8; ++kk) {
;           int ks = k8 * 8 + kk;
;           bf16x8 bfr = *(const bf16x8*)(bbase + ks * 64);
; #pragma unroll
;           for (int i = 0; i < 16; ++i)
;             acc[i] = __builtin_amdgcn_mfma_f32_16x16x32_bf16(W[(2 * kk - i) & 15], bfr, acc[i], 0, 0, 0);
.LBB0_2372:
	s_or_b32 s34, s2, s10
	s_xor_b64 s[18:19], s[8:9], -1
	s_lshl_b64 s[2:3], s[34:35], 13
	s_add_u32 s2, s55, s2
	s_addc_u32 s3, s56, s3
	v_lshl_add_u64 v[0:1], v[128:129], 4, s[2:3]
	v_lshl_add_u64 v[4:5], v[130:131], 4, s[2:3]
	global_load_dwordx4 v[0:3], v[0:1], off
	s_nop 0
	global_load_dwordx4 v[4:7], v[4:5], off offset:16
	s_waitcnt vmcnt(0)
	v_cndmask_b32_e64 v9, v5, 0, s[6:7]
	v_cndmask_b32_e64 v8, v4, 0, s[6:7]
	v_cndmask_b32_e64 v19, v7, 0, s[6:7]
	v_cndmask_b32_e64 v18, v6, 0, s[6:7]
	v_pk_mov_b32 v[4:5], v[0:1], v[2:3] op_sel:[1,0]
	v_pk_mov_b32 v[6:7], v[2:3], v[8:9] op_sel:[1,0]
	s_mov_b32 s2, 0x1000706
	ds_write_b128 v136, v[4:7] offset:16448
	v_mov_b32_e32 v6, v2
	v_mov_b32_e32 v7, v3
	ds_write_b128 v136, v[0:3]
	v_alignbit_b32 v13, v8, v3, 16
	v_perm_b32 v12, v2, v3, s2
	v_perm_b32 v11, v1, v2, s2
	v_perm_b32 v10, v0, v1, s2
	v_alignbit_b32 v17, v9, v8, 16
	ds_write_b128 v136, v[6:9] offset:32896
	v_alignbit_b32 v7, v18, v9, 16
	v_pk_mov_b32 v[0:1], v[2:3], v[8:9] op_sel:[1,0]
	v_pk_mov_b32 v[2:3], v[8:9], v[18:19] op_sel:[1,0]
	v_mov_b32_e32 v14, v11
	v_mov_b32_e32 v15, v12
	v_mov_b32_e32 v16, v13
	v_mov_b32_e32 v4, v12
	v_mov_b32_e32 v5, v13
	v_mov_b32_e32 v6, v17
	ds_write_b128 v136, v[0:3] offset:49344
	v_alignbit_b32 v3, v19, v18, 16
	v_mov_b32_e32 v0, v13
	v_mov_b32_e32 v1, v17
	v_mov_b32_e32 v2, v7
	ds_write_b128 v136, v[10:13] offset:8224
	ds_write_b128 v136, v[14:17] offset:24672
	ds_write_b128 v136, v[4:7] offset:41120
	ds_write_b128 v136, v[0:3] offset:57568
	s_waitcnt lgkmcnt(0)
	s_barrier
	ds_read_b128 v[48:51], v140
	ds_read_b128 v[44:47], v141
	ds_read_b128 v[80:83], v142
	ds_read_b128 v[52:55], v143
	ds_read_b128 v[60:63], v144
	ds_read_b128 v[56:59], v145
	ds_read_b128 v[96:99], v146
	ds_read_b128 v[64:67], v147
	ds_read_b128 v[72:75], v148
	ds_read_b128 v[68:71], v149
	ds_read_b128 v[104:107], v150
	ds_read_b128 v[76:79], v151
	ds_read_b128 v[88:91], v152
	ds_read_b128 v[84:87], v153
	ds_read_b128 v[92:95], v139
	ds_read_b128 v[100:103], v137
	s_and_b64 s[2:3], s[8:9], exec
	s_mov_b32 s2, 0x18180
	s_cselect_b32 s2, 0x10100, s2
	v_mov_b32_e32 v0, 0
	v_add3_u32 v155, s2, v138, v135
	s_mov_b32 s3, 7
	v_mov_b32_e32 v156, v154
	v_mov_b32_e32 v1, v0
	v_mov_b32_e32 v2, v0
	v_mov_b32_e32 v3, v0
	v_mov_b32_e32 v4, v0
	v_mov_b32_e32 v5, v0
	v_mov_b32_e32 v6, v0
	v_mov_b32_e32 v7, v0
	v_mov_b32_e32 v8, v0
	v_mov_b32_e32 v9, v0
	v_mov_b32_e32 v10, v0
	v_mov_b32_e32 v11, v0
	v_mov_b32_e32 v12, v0
	v_mov_b32_e32 v13, v0
	v_mov_b32_e32 v14, v0
	v_mov_b32_e32 v15, v0
	v_mov_b32_e32 v16, v0
	v_mov_b32_e32 v17, v0
	v_mov_b32_e32 v18, v0
	v_mov_b32_e32 v19, v0
	v_mov_b32_e32 v20, v0
	v_mov_b32_e32 v21, v0
	v_mov_b32_e32 v22, v0
	v_mov_b32_e32 v23, v0
	v_mov_b32_e32 v24, v0
	v_mov_b32_e32 v25, v0
	v_mov_b32_e32 v26, v0
	v_mov_b32_e32 v27, v0
	v_mov_b32_e32 v28, v0
	v_mov_b32_e32 v29, v0
	v_mov_b32_e32 v30, v0
	v_mov_b32_e32 v31, v0
	v_mov_b32_e32 v32, v0
	v_mov_b32_e32 v33, v0
	v_mov_b32_e32 v34, v0
	v_mov_b32_e32 v35, v0
	v_mov_b32_e32 v36, v0
	v_mov_b32_e32 v37, v0
	v_mov_b32_e32 v38, v0
	v_mov_b32_e32 v39, v0
	v_mov_b32_e32 v40, v0
	v_mov_b32_e32 v41, v0
	v_mov_b32_e32 v42, v0
	v_mov_b32_e32 v43, v0
	v_mov_b32_e32 v108, v0
	v_mov_b32_e32 v109, v0
	v_mov_b32_e32 v110, v0
	v_mov_b32_e32 v111, v0
	v_mov_b32_e32 v112, v0
	v_mov_b32_e32 v113, v0
	v_mov_b32_e32 v114, v0
	v_mov_b32_e32 v115, v0
	v_mov_b32_e32 v116, v0
	v_mov_b32_e32 v117, v0
	v_mov_b32_e32 v118, v0
	v_mov_b32_e32 v119, v0
	v_mov_b32_e32 v120, v0
	v_mov_b32_e32 v121, v0
	v_mov_b32_e32 v122, v0
	v_mov_b32_e32 v123, v0
	v_mov_b32_e32 v124, v0
	v_mov_b32_e32 v125, v0
	v_mov_b32_e32 v126, v0
	v_mov_b32_e32 v127, v0
	v_and_b32_e32 v166, 8, v176
	v_lshl_add_u32 v166, v166, 2, v155
	ds_read_b128 v[168:171], v155
	ds_read_b128 v[158:161], v166
	s_waitcnt lgkmcnt(0)
	s_mov_b32 exec_lo, 0xff00ff
	v_mov_b32_e32 v168, 0
	v_mov_b32_e32 v169, 0
	v_mov_b32_e32 v170, 0
	v_mov_b32_e32 v171, 0
	s_mov_b32 exec_lo, -1
	s_nop 1
	v_mfma_f32_16x16x32_bf16 v[124:127], v[84:87], v[168:171], v[124:127]
	v_mfma_f32_16x16x32_bf16 v[116:119], v[76:79], v[168:171], v[116:119]
	v_mfma_f32_16x16x32_bf16 v[108:111], v[68:71], v[168:171], v[108:111]
	v_mfma_f32_16x16x32_bf16 v[36:39], v[64:67], v[168:171], v[36:39]
	v_mfma_f32_16x16x32_bf16 v[28:31], v[56:59], v[168:171], v[28:31]
	v_mfma_f32_16x16x32_bf16 v[20:23], v[52:55], v[168:171], v[20:23]
	v_mfma_f32_16x16x32_bf16 v[12:15], v[44:47], v[168:171], v[12:15]
	v_mfma_f32_16x16x32_bf16 v[4:7], v[92:95], v[168:171], v[4:7]
	s_branch .LBB0_2374

; __device__ __forceinline__ void hyena_item(cchar4* ka, int L, int c, char* smem) {
;     ...
;     {
;       const char* wbase = cop + lane_base - 512 * wave;
;       const char* bbase = Bs + (fr & 7) * USTR + 16 * g;
;       bf16x8 W[16];
; #pragma unroll
;       for (int u = -15; u <= 0; ++u) W[u & 15] = *(const bf16x8*)(wbase + 32 * u);
; #pragma unroll 1
;       for (int k8 = 0; k8 < 8; ++k8) {
; #pragma unroll
;         for (int kk = 0; kk < 8; ++kk) {
;           int ks = k8 * 8 + kk;
;           bf16x8 bfr = *(const bf16x8*)(bbase + ks * 64);
; #pragma unroll
;           for (int i = 0; i < 16; ++i)
;             acc[i] = __builtin_amdgcn_mfma_f32_16x16x32_bf16(W[(2 * kk - i) & 15], bfr, acc[i], 0, 0, 0);
;           if (ks < 63) {
;             W[(2 * kk + 1) & 15] = *(const bf16x8*)(wbase + 32 * (2 * ks + 1));
;             W[(2 * kk + 2) & 15] = *(const bf16x8*)(wbase + 32 * (2 * ks + 2));
;           }
;         }
;       }
.LBB0_2374:
	s_waitcnt lgkmcnt(0)
	v_mfma_f32_16x16x32_bf16 v[4:7], v[48:51], v[158:161], v[4:7]
	ds_read_b128 v[48:51], v156 offset:32
	ds_read_b128 v[162:165], v166 offset:64
	v_mfma_f32_16x16x32_bf16 v[124:127], v[100:103], v[158:161], v[124:127]
	v_mfma_f32_16x16x32_bf16 v[116:119], v[88:91], v[158:161], v[116:119]
	v_mfma_f32_16x16x32_bf16 v[108:111], v[104:107], v[158:161], v[108:111]
	v_mfma_f32_16x16x32_bf16 v[36:39], v[72:75], v[158:161], v[36:39]
	v_mfma_f32_16x16x32_bf16 v[28:31], v[96:99], v[158:161], v[28:31]
	v_mfma_f32_16x16x32_bf16 v[20:23], v[60:63], v[158:161], v[20:23]
	v_mfma_f32_16x16x32_bf16 v[12:15], v[80:83], v[158:161], v[12:15]
	s_waitcnt lgkmcnt(0)
	v_mfma_f32_16x16x32_bf16 v[4:7], v[80:83], v[162:165], v[4:7]
	ds_read_b128 v[80:83], v156 offset:96
	ds_read_b128 v[158:161], v166 offset:128
	v_mfma_f32_16x16x32_bf16 v[124:127], v[48:51], v[162:165], v[124:127]
	v_mfma_f32_16x16x32_bf16 v[116:119], v[100:103], v[162:165], v[116:119]
	v_mfma_f32_16x16x32_bf16 v[108:111], v[88:91], v[162:165], v[108:111]
	v_mfma_f32_16x16x32_bf16 v[36:39], v[104:107], v[162:165], v[36:39]
	v_mfma_f32_16x16x32_bf16 v[28:31], v[72:75], v[162:165], v[28:31]
	v_mfma_f32_16x16x32_bf16 v[20:23], v[96:99], v[162:165], v[20:23]
	v_mfma_f32_16x16x32_bf16 v[12:15], v[60:63], v[162:165], v[12:15]
	s_waitcnt lgkmcnt(0)
	v_mfma_f32_16x16x32_bf16 v[4:7], v[60:63], v[158:161], v[4:7]
	ds_read_b128 v[60:63], v156 offset:160
	ds_read_b128 v[162:165], v166 offset:192
	v_mfma_f32_16x16x32_bf16 v[124:127], v[80:83], v[158:161], v[124:127]
	v_mfma_f32_16x16x32_bf16 v[116:119], v[48:51], v[158:161], v[116:119]
	v_mfma_f32_16x16x32_bf16 v[108:111], v[100:103], v[158:161], v[108:111]
	v_mfma_f32_16x16x32_bf16 v[36:39], v[88:91], v[158:161], v[36:39]
	v_mfma_f32_16x16x32_bf16 v[28:31], v[104:107], v[158:161], v[28:31]
	v_mfma_f32_16x16x32_bf16 v[20:23], v[72:75], v[158:161], v[20:23]
	v_mfma_f32_16x16x32_bf16 v[12:15], v[96:99], v[158:161], v[12:15]
	s_waitcnt lgkmcnt(0)
	v_mfma_f32_16x16x32_bf16 v[4:7], v[96:99], v[162:165], v[4:7]
	ds_read_b128 v[96:99], v156 offset:224
	ds_read_b128 v[158:161], v166 offset:256
	v_mfma_f32_16x16x32_bf16 v[124:127], v[60:63], v[162:165], v[124:127]
	v_mfma_f32_16x16x32_bf16 v[116:119], v[80:83], v[162:165], v[116:119]
	v_mfma_f32_16x16x32_bf16 v[108:111], v[48:51], v[162:165], v[108:111]
	v_mfma_f32_16x16x32_bf16 v[36:39], v[100:103], v[162:165], v[36:39]
	v_mfma_f32_16x16x32_bf16 v[28:31], v[88:91], v[162:165], v[28:31]
	v_mfma_f32_16x16x32_bf16 v[20:23], v[104:107], v[162:165], v[20:23]
	v_mfma_f32_16x16x32_bf16 v[12:15], v[72:75], v[162:165], v[12:15]
	s_waitcnt lgkmcnt(0)
	v_mfma_f32_16x16x32_bf16 v[4:7], v[72:75], v[158:161], v[4:7]
	ds_read_b128 v[72:75], v156 offset:288
	ds_read_b128 v[162:165], v166 offset:320
	v_mfma_f32_16x16x32_bf16 v[124:127], v[96:99], v[158:161], v[124:127]
	v_mfma_f32_16x16x32_bf16 v[116:119], v[60:63], v[158:161], v[116:119]
	v_mfma_f32_16x16x32_bf16 v[108:111], v[80:83], v[158:161], v[108:111]
	v_mfma_f32_16x16x32_bf16 v[36:39], v[48:51], v[158:161], v[36:39]
	v_mfma_f32_16x16x32_bf16 v[28:31], v[100:103], v[158:161], v[28:31]
	v_mfma_f32_16x16x32_bf16 v[20:23], v[88:91], v[158:161], v[20:23]
	v_mfma_f32_16x16x32_bf16 v[12:15], v[104:107], v[158:161], v[12:15]
	s_waitcnt lgkmcnt(0)
	v_mfma_f32_16x16x32_bf16 v[4:7], v[104:107], v[162:165], v[4:7]
	ds_read_b128 v[104:107], v156 offset:352
	ds_read_b128 v[158:161], v166 offset:384
	v_mfma_f32_16x16x32_bf16 v[124:127], v[72:75], v[162:165], v[124:127]
	v_mfma_f32_16x16x32_bf16 v[116:119], v[96:99], v[162:165], v[116:119]
	v_mfma_f32_16x16x32_bf16 v[108:111], v[60:63], v[162:165], v[108:111]
	v_mfma_f32_16x16x32_bf16 v[36:39], v[80:83], v[162:165], v[36:39]
	v_mfma_f32_16x16x32_bf16 v[28:31], v[48:51], v[162:165], v[28:31]
	v_mfma_f32_16x16x32_bf16 v[20:23], v[100:103], v[162:165], v[20:23]
	v_mfma_f32_16x16x32_bf16 v[12:15], v[88:91], v[162:165], v[12:15]
	s_waitcnt lgkmcnt(0)
	v_mfma_f32_16x16x32_bf16 v[4:7], v[88:91], v[158:161], v[4:7]
	ds_read_b128 v[88:91], v156 offset:416
	ds_read_b128 v[162:165], v166 offset:448
	v_mfma_f32_16x16x32_bf16 v[124:127], v[104:107], v[158:161], v[124:127]
	v_mfma_f32_16x16x32_bf16 v[116:119], v[72:75], v[158:161], v[116:119]
	v_mfma_f32_16x16x32_bf16 v[108:111], v[96:99], v[158:161], v[108:111]
	v_mfma_f32_16x16x32_bf16 v[36:39], v[60:63], v[158:161], v[36:39]
	v_mfma_f32_16x16x32_bf16 v[28:31], v[80:83], v[158:161], v[28:31]
	v_mfma_f32_16x16x32_bf16 v[20:23], v[48:51], v[158:161], v[20:23]
	v_mfma_f32_16x16x32_bf16 v[12:15], v[100:103], v[158:161], v[12:15]
	s_waitcnt lgkmcnt(0)
	s_cmp_lg_u32 s3, 63
	s_cbranch_scc1 .Lhy2_nomask
	s_mov_b32 exec_lo, 0
	s_mov_b32 exec_hi, 0xff00ff00
	v_mov_b32_e32 v162, 0
	v_mov_b32_e32 v163, 0
	v_mov_b32_e32 v164, 0
	v_mov_b32_e32 v165, 0
	s_mov_b64 exec, -1
	s_nop 1
.Lhy2_nomask:
	v_mfma_f32_16x16x32_bf16 v[4:7], v[100:103], v[162:165], v[4:7]
	s_cmp_lt_u32 s3, 63
	s_cbranch_scc0 .Lhy2_skip_pf
	ds_read_b128 v[100:103], v156 offset:480
	ds_read_b128 v[158:161], v166 offset:512
.Lhy2_skip_pf:
	v_mfma_f32_16x16x32_bf16 v[124:127], v[88:91], v[162:165], v[124:127]
	v_mfma_f32_16x16x32_bf16 v[116:119], v[104:107], v[162:165], v[116:119]
	v_mfma_f32_16x16x32_bf16 v[108:111], v[72:75], v[162:165], v[108:111]
	v_mfma_f32_16x16x32_bf16 v[36:39], v[96:99], v[162:165], v[36:39]
	v_mfma_f32_16x16x32_bf16 v[28:31], v[60:63], v[162:165], v[28:31]
	v_mfma_f32_16x16x32_bf16 v[20:23], v[80:83], v[162:165], v[20:23]
	v_mfma_f32_16x16x32_bf16 v[12:15], v[48:51], v[162:165], v[12:15]
	v_add_u32_e32 v166, 0x200, v166
	s_branch .LBB0_2373
; __device__ __forceinline__ float lo16(unsigned u) { return __uint_as_float(u << 16); }
; __device__ __forceinline__ float hi16(unsigned u) { return __uint_as_float(u & 0xffff0000u); }
; #define SCHED __builtin_amdgcn_sched_barrier(0)
; __device__ __forceinline__ void hyena_item(cchar4* ka, int L, int c, char* smem) {
;     ...
;     {
;       int wv = wave, gg = g, frr = fr;
;       asm volatile("" : "+v"(wv), "+v"(gg), "+v"(frr));
;       if (frr < 8) {
;         int b = frr;
;         int col = (order == 0) ? c : (512 + c);
;         float s0 = sw[col], s1 = sw[1536 + col], s2 = sw[3072 + col], sb = sbp[col];
;         float bias = hb[order * 512 + c];
;         const u16* pr = PCT + ((size_t)b * 1536 + col) * 2048;
;         const char* ub = Bs + b * USTR;
;         char* zb = Zs + b * USTR;
;         u16* yb = Y2T + (size_t)c * T + (size_t)b * 2048;
; #pragma unroll
;         for (int i4 = 0; i4 < 16; i4 += 4) {
;           uint2 pwv[4], uwv[4]; unsigned plv[4], prv[4];
; #pragma unroll
;           for (int ii = 0; ii < 4; ++ii) {
;             int t0 = (wv * 16 + i4 + ii) * 16 + 4 * gg;
;             pwv[ii] = *(const uint2*)(pr + t0);
;             plv[ii] = pr[t0 > 0 ? t0 - 1 : 0];
;             prv[ii] = pr[t0 + 4 < 2048 ? t0 + 4 : 2047];
;             uwv[ii] = *(const uint2*)(ub + t0 * 2);
;           }
;           SCHED;
; #pragma unroll
;           for (int ii = 0; ii < 4; ++ii) {
;             const int i = i4 + ii;
;             int t0 = (wv * 16 + i) * 16 + 4 * gg;
;             float pv[6];
;             pv[0] = t0 > 0 ? lo16(plv[ii]) : 0.f;
;             pv[1] = lo16(pwv[ii].x); pv[2] = hi16(pwv[ii].x); pv[3] = lo16(pwv[ii].y); pv[4] = hi16(pwv[ii].y);
;             pv[5] = (t0 + 4 < 2048) ? lo16(prv[ii]) : 0.f;
;             float uu[4] = {lo16(uwv[ii].x), hi16(uwv[ii].x), lo16(uwv[ii].y), hi16(uwv[ii].y)};
;             float val[4];
; #pragma unroll
;             for (int j = 0; j < 4; ++j) {
;               float xg = s0 * pv[j] + s1 * pv[j + 1] + s2 * pv[j + 2] + sb;
;               val[j] = xg * (acc[i][j] + uu[j] * bias);
;             }
;             uint2 zw; zw.x = pack2(val[0], val[1]); zw.y = pack2(val[2], val[3]);
;             if (order == 0) *(uint2*)(zb + t0 * 2) = zw;
;             else *(uint2*)(yb + t0) = zw;
.LBB0_2376:
	s_nop 7
	s_nop 7
	v_mov_b32_dpp v120, v124 row_ror:8 row_mask:0xf bank_mask:0xf
	v_mov_b32_dpp v121, v125 row_ror:8 row_mask:0xf bank_mask:0xf
	v_mov_b32_dpp v122, v126 row_ror:8 row_mask:0xf bank_mask:0xf
	v_mov_b32_dpp v123, v127 row_ror:8 row_mask:0xf bank_mask:0xf
	v_mov_b32_dpp v112, v116 row_ror:8 row_mask:0xf bank_mask:0xf
	v_mov_b32_dpp v113, v117 row_ror:8 row_mask:0xf bank_mask:0xf
	v_mov_b32_dpp v114, v118 row_ror:8 row_mask:0xf bank_mask:0xf
	v_mov_b32_dpp v115, v119 row_ror:8 row_mask:0xf bank_mask:0xf
	v_mov_b32_dpp v40, v108 row_ror:8 row_mask:0xf bank_mask:0xf
	v_mov_b32_dpp v41, v109 row_ror:8 row_mask:0xf bank_mask:0xf
	v_mov_b32_dpp v42, v110 row_ror:8 row_mask:0xf bank_mask:0xf
	v_mov_b32_dpp v43, v111 row_ror:8 row_mask:0xf bank_mask:0xf
	v_mov_b32_dpp v32, v36 row_ror:8 row_mask:0xf bank_mask:0xf
	v_mov_b32_dpp v33, v37 row_ror:8 row_mask:0xf bank_mask:0xf
	v_mov_b32_dpp v34, v38 row_ror:8 row_mask:0xf bank_mask:0xf
	v_mov_b32_dpp v35, v39 row_ror:8 row_mask:0xf bank_mask:0xf
	v_mov_b32_dpp v24, v28 row_ror:8 row_mask:0xf bank_mask:0xf
	v_mov_b32_dpp v25, v29 row_ror:8 row_mask:0xf bank_mask:0xf
	v_mov_b32_dpp v26, v30 row_ror:8 row_mask:0xf bank_mask:0xf
	v_mov_b32_dpp v27, v31 row_ror:8 row_mask:0xf bank_mask:0xf
	v_mov_b32_dpp v16, v20 row_ror:8 row_mask:0xf bank_mask:0xf
	v_mov_b32_dpp v17, v21 row_ror:8 row_mask:0xf bank_mask:0xf
	v_mov_b32_dpp v18, v22 row_ror:8 row_mask:0xf bank_mask:0xf
	v_mov_b32_dpp v19, v23 row_ror:8 row_mask:0xf bank_mask:0xf
	v_mov_b32_dpp v8, v12 row_ror:8 row_mask:0xf bank_mask:0xf
	v_mov_b32_dpp v9, v13 row_ror:8 row_mask:0xf bank_mask:0xf
	v_mov_b32_dpp v10, v14 row_ror:8 row_mask:0xf bank_mask:0xf
	v_mov_b32_dpp v11, v15 row_ror:8 row_mask:0xf bank_mask:0xf
	v_mov_b32_dpp v0, v4 row_ror:8 row_mask:0xf bank_mask:0xf
	v_mov_b32_dpp v1, v5 row_ror:8 row_mask:0xf bank_mask:0xf
	v_mov_b32_dpp v2, v6 row_ror:8 row_mask:0xf bank_mask:0xf
	v_mov_b32_dpp v3, v7 row_ror:8 row_mask:0xf bank_mask:0xf
	v_mov_b32_e32 v47, v132
	v_mov_b32_e32 v54, v133
	v_mov_b32_e32 v49, v134
	s_nop 0
	v_cmp_gt_i32_e32 vcc, 8, v54
	s_and_saveexec_b64 s[48:49], vcc
	s_cbranch_execz .LBB0_2371
	s_and_b64 s[8:9], s[8:9], exec
	s_cselect_b32 s8, s10, s53
	s_mov_b32 s9, s35
	v_mov_b64_e32 v[52:53], s[8:9]
	s_movk_i32 s3, 0x600
	s_lshl_b64 s[16:17], s[8:9], 2
	v_mad_i64_i32 v[52:53], s[8:9], v54, s3, v[52:53]
	v_lshlrev_b64 v[52:53], 12, v[52:53]
	v_lshlrev_b32_e32 v58, 8, v47
	v_lshlrev_b32_e32 v60, 2, v49
	v_lshl_add_u64 v[56:57], s[20:21], 0, v[52:53]
	v_add_u32_e32 v52, v60, v58
	v_min_i32_e32 v64, 0x7fb, v52
	v_ashrrev_i32_e32 v53, 31, v52
	v_max_i32_e32 v47, 1, v52
	v_ashrrev_i32_e32 v65, 31, v64
	v_add_u32_e32 v55, 16, v52
	v_lshl_add_u64 v[62:63], v[52:53], 1, v[56:57]
	v_lshlrev_b32_e32 v178, 1, v47
	v_lshl_add_u64 v[64:65], v[64:65], 1, v[56:57]
	v_max_i32_e32 v47, 1, v55
	global_load_dwordx2 v[72:73], v[62:63], off
	global_load_ushort v82, v[64:65], off offset:8
	v_lshl_add_u64 v[62:63], v[56:57], 0, v[178:179]
	v_lshlrev_b32_e32 v178, 1, v47
	v_lshl_add_u64 v[64:65], v[56:57], 0, v[178:179]
	global_load_ushort v47, v[64:65], off offset:-2
	v_min_i32_e32 v64, 0x7fb, v55
	v_add_u32_e32 v70, 32, v52
	v_ashrrev_i32_e32 v65, 31, v64
	v_max_i32_e32 v51, 1, v70
	v_lshl_add_u64 v[64:65], v[64:65], 1, v[56:57]
	v_lshlrev_b32_e32 v178, 1, v51
	s_add_u32 vcc_lo, s58, s16
	global_load_ushort v49, v[64:65], off offset:8
	v_lshl_add_u64 v[64:65], v[56:57], 0, v[178:179]
	v_add_u32_e32 v83, 48, v52
	s_addc_u32 vcc_hi, s44, s17
	v_ashrrev_i32_e32 v61, 31, v60
	v_ashrrev_i32_e32 v59, 31, v58
	global_load_ushort v76, v[64:65], off offset:-2
	v_min_i32_e32 v64, 0x7fb, v70
	v_max_i32_e32 v51, 1, v83
	s_add_u32 s16, s45, s16
	v_lshl_add_u64 v[58:59], v[58:59], 0, v[60:61]
	v_ashrrev_i32_e32 v65, 31, v64
	v_lshlrev_b32_e32 v178, 1, v51
	s_addc_u32 s17, s46, s17
	v_lshl_add_u64 v[58:59], v[58:59], 1, v[56:57]
	v_lshl_add_u64 v[64:65], v[64:65], 1, v[56:57]
	v_lshl_add_u64 v[68:69], v[56:57], 0, v[178:179]
	global_load_dword v45, v179, vcc
	global_load_dword v48, v179, s[16:17]
	s_lshl_b64 s[16:17], s[34:35], 2
	global_load_dwordx2 v[60:61], v[58:59], off offset:32
	global_load_dwordx2 v[66:67], v[58:59], off offset:64
	global_load_ushort v74, v[68:69], off offset:-2
	global_load_ushort v77, v[64:65], off offset:8
	v_min_i32_e32 v68, 0x7fb, v83
	global_load_dwordx2 v[64:65], v[58:59], off offset:96
	s_add_u32 s16, s11, s16
	v_ashrrev_i32_e32 v69, 31, v68
	v_mov_b32_e32 v44, 0x1000
	v_mov_b32_e32 v46, 0x3000
	s_addc_u32 s17, s47, s17
	v_lshl_add_u64 v[68:69], v[68:69], 1, v[56:57]
	global_load_dword v44, v44, vcc offset:2048
	v_mul_lo_u32 v79, v54, s33
	global_load_dword v46, v46, vcc
	v_add_u32_e32 v78, s2, v79
	global_load_dword v50, v179, s[16:17]
	global_load_ushort v75, v[68:69], off offset:8
	s_waitcnt lgkmcnt(1)
	global_load_ushort v84, v[62:63], off offset:-2
	v_lshlrev_b32_e32 v51, 1, v52
	v_add_u32_e32 v62, v78, v51
	v_lshl_add_u32 v55, v55, 1, v78
	ds_read_b64 v[80:81], v62
	ds_read_b64 v[62:63], v55
	v_lshl_add_u32 v55, v70, 1, v78
	ds_read_b64 v[70:71], v55
	v_lshl_add_u32 v55, v83, 1, v78
	ds_read_b64 v[68:69], v55
	v_ashrrev_i32_e32 v55, 31, v54
	v_lshlrev_b64 v[54:55], 12, v[54:55]
	v_lshl_add_u64 v[54:55], s[12:13], 0, v[54:55]
	s_waitcnt vmcnt(0)
	v_lshlrev_b32_e32 v83, 16, v84
	v_cmp_lt_i32_e32 vcc, 0, v52
	v_lshlrev_b32_e32 v84, 16, v72
	v_and_b32_e32 v72, 0xffff0000, v72
	v_cndmask_b32_e32 v83, 0, v83, vcc
	v_mul_f32_e32 v83, v45, v83
	v_fmac_f32_e32 v83, v44, v84
	s_waitcnt lgkmcnt(3)
	v_lshlrev_b32_e32 v86, 16, v80
	v_fmac_f32_e32 v83, v46, v72
	v_add_f32_e32 v83, v48, v83
	v_fma_f32 v86, v50, v86, v124
	v_mul_f32_e32 v83, v86, v83
	v_mul_f32_e32 v86, v44, v72
	v_lshlrev_b32_e32 v85, 16, v73
	v_fmac_f32_e32 v86, v45, v84
	v_and_b32_e32 v80, 0xffff0000, v80
	v_fmac_f32_e32 v86, v46, v85
	v_add_f32_e32 v84, v48, v86
	v_fma_f32 v80, v50, v80, v125
	v_mul_f32_e32 v80, v84, v80
	v_mul_f32_e32 v84, v44, v85
	v_and_b32_e32 v73, 0xffff0000, v73
	v_fmac_f32_e32 v84, v45, v72
	v_lshlrev_b32_e32 v87, 16, v81
	v_fmac_f32_e32 v84, v46, v73
	s_movk_i32 s2, 0x7fc
	v_add_f32_e32 v72, v48, v84
	v_fma_f32 v84, v50, v87, v126
	v_lshlrev_b32_e32 v82, 16, v82
	v_cmp_gt_i32_e32 vcc, s2, v52
	v_mul_f32_e32 v84, v72, v84
	v_mul_f32_e32 v72, v44, v73
	v_cndmask_b32_e32 v82, 0, v82, vcc
	v_fmac_f32_e32 v72, v45, v85
	v_and_b32_e32 v81, 0xffff0000, v81
	v_fmac_f32_e32 v72, v46, v82
	v_add_f32_e32 v72, v48, v72
	v_fmac_f32_e32 v127, v50, v81
	v_mul_f32_e32 v73, v72, v127
	v_cvt_pk_bf16_f32 v72, v83, v80
	v_cvt_pk_bf16_f32 v73, v84, v73
	s_mov_b64 s[8:9], -1
	s_and_b64 vcc, exec, s[18:19]
	v_lshl_add_u64 v[54:55], v[52:53], 1, v[54:55]
	s_cbranch_vccz .LBB0_2379
	global_store_dwordx2 v[54:55], v[72:73], off
	s_mov_b64 s[8:9], 0
